# attention row sums with packed f32 adds (same accumulation order)
# speedup vs baseline: 1.0070x; 1.0001x over previous
.Lat2_back_8:
	v_exp_f32_e32 v64, v64
	v_exp_f32_e32 v65, v65
	v_exp_f32_e32 v66, v66
	v_exp_f32_e32 v67, v67
	v_exp_f32_e32 v68, v68
	v_exp_f32_e32 v69, v69
	v_exp_f32_e32 v70, v70
	v_exp_f32_e32 v71, v71
	s_nop 0
	v_pk_add_f32 v[232:233], v[232:233], v[64:65]
	v_pk_add_f32 v[234:235], v[234:235], v[66:67]
	v_pk_add_f32 v[232:233], v[232:233], v[68:69]
	v_pk_add_f32 v[234:235], v[234:235], v[70:71]
	v_cvt_pk_bf16_f32 v64, v64, v65
	v_cvt_pk_bf16_f32 v65, v66, v67
	v_cvt_pk_bf16_f32 v66, v68, v69
	v_cvt_pk_bf16_f32 v67, v70, v71
	s_waitcnt lgkmcnt(0)
	s_nop 0
	v_mfma_f32_32x32x16_bf16 v[0:15], v[64:67], v[164:167], v[0:15]
	v_exp_f32_e32 v72, v72
	v_exp_f32_e32 v73, v73
	v_mfma_f32_32x32x16_bf16 v[16:31], v[64:67], v[168:171], v[16:31]
	ds_read_b64_tr_b16 v[164:165], v206 offset:2048
	ds_read_b64_tr_b16 v[166:167], v206 offset:2560
	v_exp_f32_e32 v74, v74
	v_exp_f32_e32 v75, v75
	v_pk_add_f32 v[232:233], v[232:233], v[72:73]
	v_mfma_f32_32x32x16_bf16 v[32:47], v[64:67], v[172:175], v[32:47]
	ds_read_b64_tr_b16 v[168:169], v206 offset:6144
	ds_read_b64_tr_b16 v[170:171], v206 offset:6656
	v_exp_f32_e32 v76, v76
	v_exp_f32_e32 v77, v77
	v_pk_add_f32 v[234:235], v[234:235], v[74:75]
	v_mfma_f32_32x32x16_bf16 v[48:63], v[64:67], v[176:179], v[48:63]
	ds_read_b64_tr_b16 v[172:173], v206 offset:10240
	ds_read_b64_tr_b16 v[174:175], v206 offset:10752
	v_exp_f32_e32 v78, v78
	v_exp_f32_e32 v79, v79
	v_pk_add_f32 v[232:233], v[232:233], v[76:77]
	s_nop 0
	v_pk_add_f32 v[234:235], v[234:235], v[78:79]
	v_cvt_pk_bf16_f32 v72, v72, v73
	v_cvt_pk_bf16_f32 v73, v74, v75
	v_cvt_pk_bf16_f32 v74, v76, v77
	v_cvt_pk_bf16_f32 v75, v78, v79
	s_nop 1
	v_mfma_f32_32x32x16_bf16 v[0:15], v[72:75], v[180:183], v[0:15]
	ds_read_b64_tr_b16 v[176:177], v206 offset:14336
	ds_read_b64_tr_b16 v[178:179], v206 offset:14848
	v_exp_f32_e32 v80, v80
	v_exp_f32_e32 v81, v81
	v_mfma_f32_32x32x16_bf16 v[16:31], v[72:75], v[184:187], v[16:31]
	ds_read_b64_tr_b16 v[180:181], v206 offset:3072
	ds_read_b64_tr_b16 v[182:183], v206 offset:3584
	v_exp_f32_e32 v82, v82
	v_exp_f32_e32 v83, v83
	v_pk_add_f32 v[232:233], v[232:233], v[80:81]
	v_mfma_f32_32x32x16_bf16 v[32:47], v[72:75], v[188:191], v[32:47]
	ds_read_b64_tr_b16 v[184:185], v206 offset:7168
	ds_read_b64_tr_b16 v[186:187], v206 offset:7680
	v_exp_f32_e32 v84, v84
	v_exp_f32_e32 v85, v85
	v_pk_add_f32 v[234:235], v[234:235], v[82:83]
	v_mfma_f32_32x32x16_bf16 v[48:63], v[72:75], v[192:195], v[48:63]
	ds_read_b64_tr_b16 v[188:189], v206 offset:11264
	ds_read_b64_tr_b16 v[190:191], v206 offset:11776
	v_exp_f32_e32 v86, v86
	v_exp_f32_e32 v87, v87
	v_pk_add_f32 v[232:233], v[232:233], v[84:85]
	s_nop 0
	v_pk_add_f32 v[234:235], v[234:235], v[86:87]
	v_cvt_pk_bf16_f32 v80, v80, v81
	v_cvt_pk_bf16_f32 v81, v82, v83
	v_cvt_pk_bf16_f32 v82, v84, v85
	v_cvt_pk_bf16_f32 v83, v86, v87
	s_nop 1
	s_waitcnt lgkmcnt(12)
	v_mfma_f32_32x32x16_bf16 v[0:15], v[80:83], v[164:167], v[0:15]
	ds_read_b64_tr_b16 v[192:193], v206 offset:15360
	ds_read_b64_tr_b16 v[194:195], v206 offset:15872
	v_exp_f32_e32 v88, v88
	v_exp_f32_e32 v89, v89
	s_waitcnt lgkmcnt(12)
	v_mfma_f32_32x32x16_bf16 v[16:31], v[80:83], v[168:171], v[16:31]
	v_exp_f32_e32 v90, v90
	v_exp_f32_e32 v91, v91
	v_pk_add_f32 v[232:233], v[232:233], v[88:89]
	s_waitcnt lgkmcnt(10)
	v_mfma_f32_32x32x16_bf16 v[32:47], v[80:83], v[172:175], v[32:47]
	v_exp_f32_e32 v92, v92
	v_exp_f32_e32 v93, v93
	v_pk_add_f32 v[234:235], v[234:235], v[90:91]
	s_waitcnt lgkmcnt(8)
	v_mfma_f32_32x32x16_bf16 v[48:63], v[80:83], v[176:179], v[48:63]
	v_exp_f32_e32 v94, v94
	v_exp_f32_e32 v95, v95
	v_pk_add_f32 v[232:233], v[232:233], v[92:93]
	s_nop 0
	v_pk_add_f32 v[234:235], v[234:235], v[94:95]
	v_cvt_pk_bf16_f32 v88, v88, v89
	v_cvt_pk_bf16_f32 v89, v90, v91
	v_cvt_pk_bf16_f32 v90, v92, v93
	v_cvt_pk_bf16_f32 v91, v94, v95
	s_nop 1
	s_waitcnt lgkmcnt(6)
	v_mfma_f32_32x32x16_bf16 v[0:15], v[88:91], v[180:183], v[0:15]
	s_waitcnt lgkmcnt(4)
	v_mfma_f32_32x32x16_bf16 v[16:31], v[88:91], v[184:187], v[16:31]
	s_waitcnt lgkmcnt(2)
	v_mfma_f32_32x32x16_bf16 v[32:47], v[88:91], v[188:191], v[32:47]
	s_waitcnt lgkmcnt(0)
	v_mfma_f32_32x32x16_bf16 v[48:63], v[88:91], v[192:195], v[48:63]
	s_add_i32 s6, s45, 3
	s_cmp_lt_u32 s6, s39
	s_cbranch_scc1 .Lat2_w6_16
	s_cmp_eq_u32 s6, s39
	s_cbranch_scc1 .Lat2_w3_14
	s_waitcnt vmcnt(0)
	s_branch .Lat2_wd_15

.Lat2_back_19:
	v_exp_f32_e32 v64, v64
	v_exp_f32_e32 v65, v65
	v_exp_f32_e32 v66, v66
	v_exp_f32_e32 v67, v67
	v_exp_f32_e32 v68, v68
	v_exp_f32_e32 v69, v69
	v_exp_f32_e32 v70, v70
	v_exp_f32_e32 v71, v71
	s_nop 0
	v_pk_add_f32 v[232:233], v[232:233], v[64:65]
	v_pk_add_f32 v[234:235], v[234:235], v[66:67]
	v_pk_add_f32 v[232:233], v[232:233], v[68:69]
	v_pk_add_f32 v[234:235], v[234:235], v[70:71]
	v_cvt_pk_bf16_f32 v64, v64, v65
	v_cvt_pk_bf16_f32 v65, v66, v67
	v_cvt_pk_bf16_f32 v66, v68, v69
	v_cvt_pk_bf16_f32 v67, v70, v71
	s_waitcnt lgkmcnt(0)
	s_nop 0
	v_mfma_f32_32x32x16_bf16 v[0:15], v[64:67], v[164:167], v[0:15]
	v_exp_f32_e32 v72, v72
	v_exp_f32_e32 v73, v73
	v_mfma_f32_32x32x16_bf16 v[16:31], v[64:67], v[168:171], v[16:31]
	ds_read_b64_tr_b16 v[164:165], v206 offset:2048
	ds_read_b64_tr_b16 v[166:167], v206 offset:2560
	v_exp_f32_e32 v74, v74
	v_exp_f32_e32 v75, v75
	v_pk_add_f32 v[232:233], v[232:233], v[72:73]
	v_mfma_f32_32x32x16_bf16 v[32:47], v[64:67], v[172:175], v[32:47]
	ds_read_b64_tr_b16 v[168:169], v206 offset:6144
	ds_read_b64_tr_b16 v[170:171], v206 offset:6656
	v_exp_f32_e32 v76, v76
	v_exp_f32_e32 v77, v77
	v_pk_add_f32 v[234:235], v[234:235], v[74:75]
	v_mfma_f32_32x32x16_bf16 v[48:63], v[64:67], v[176:179], v[48:63]
	ds_read_b64_tr_b16 v[172:173], v206 offset:10240
	ds_read_b64_tr_b16 v[174:175], v206 offset:10752
	v_exp_f32_e32 v78, v78
	v_exp_f32_e32 v79, v79
	v_pk_add_f32 v[232:233], v[232:233], v[76:77]
	s_nop 0
	v_pk_add_f32 v[234:235], v[234:235], v[78:79]
	v_cvt_pk_bf16_f32 v72, v72, v73
	v_cvt_pk_bf16_f32 v73, v74, v75
	v_cvt_pk_bf16_f32 v74, v76, v77
	v_cvt_pk_bf16_f32 v75, v78, v79
	s_nop 1
	v_mfma_f32_32x32x16_bf16 v[0:15], v[72:75], v[180:183], v[0:15]
	ds_read_b64_tr_b16 v[176:177], v206 offset:14336
	ds_read_b64_tr_b16 v[178:179], v206 offset:14848
	v_exp_f32_e32 v80, v80
	v_exp_f32_e32 v81, v81
	v_mfma_f32_32x32x16_bf16 v[16:31], v[72:75], v[184:187], v[16:31]
	ds_read_b64_tr_b16 v[180:181], v206 offset:3072
	ds_read_b64_tr_b16 v[182:183], v206 offset:3584
	v_exp_f32_e32 v82, v82
	v_exp_f32_e32 v83, v83
	v_pk_add_f32 v[232:233], v[232:233], v[80:81]
	v_mfma_f32_32x32x16_bf16 v[32:47], v[72:75], v[188:191], v[32:47]
	ds_read_b64_tr_b16 v[184:185], v206 offset:7168
	ds_read_b64_tr_b16 v[186:187], v206 offset:7680
	v_exp_f32_e32 v84, v84
	v_exp_f32_e32 v85, v85
	v_pk_add_f32 v[234:235], v[234:235], v[82:83]
	v_mfma_f32_32x32x16_bf16 v[48:63], v[72:75], v[192:195], v[48:63]
	ds_read_b64_tr_b16 v[188:189], v206 offset:11264
	ds_read_b64_tr_b16 v[190:191], v206 offset:11776
	v_exp_f32_e32 v86, v86
	v_exp_f32_e32 v87, v87
	v_pk_add_f32 v[232:233], v[232:233], v[84:85]
	s_nop 0
	v_pk_add_f32 v[234:235], v[234:235], v[86:87]
	v_cvt_pk_bf16_f32 v80, v80, v81
	v_cvt_pk_bf16_f32 v81, v82, v83
	v_cvt_pk_bf16_f32 v82, v84, v85
	v_cvt_pk_bf16_f32 v83, v86, v87
	s_nop 1
	s_waitcnt lgkmcnt(12)
	v_mfma_f32_32x32x16_bf16 v[0:15], v[80:83], v[164:167], v[0:15]
	ds_read_b64_tr_b16 v[192:193], v206 offset:15360
	ds_read_b64_tr_b16 v[194:195], v206 offset:15872
	v_exp_f32_e32 v88, v88
	v_exp_f32_e32 v89, v89
	s_waitcnt lgkmcnt(12)
	v_mfma_f32_32x32x16_bf16 v[16:31], v[80:83], v[168:171], v[16:31]
	v_exp_f32_e32 v90, v90
	v_exp_f32_e32 v91, v91
	v_pk_add_f32 v[232:233], v[232:233], v[88:89]
	s_waitcnt lgkmcnt(10)
	v_mfma_f32_32x32x16_bf16 v[32:47], v[80:83], v[172:175], v[32:47]
	v_exp_f32_e32 v92, v92
	v_exp_f32_e32 v93, v93
	v_pk_add_f32 v[234:235], v[234:235], v[90:91]
	s_waitcnt lgkmcnt(8)
	v_mfma_f32_32x32x16_bf16 v[48:63], v[80:83], v[176:179], v[48:63]
	v_exp_f32_e32 v94, v94
	v_exp_f32_e32 v95, v95
	v_pk_add_f32 v[232:233], v[232:233], v[92:93]
	s_nop 0
	v_pk_add_f32 v[234:235], v[234:235], v[94:95]
	v_cvt_pk_bf16_f32 v88, v88, v89
	v_cvt_pk_bf16_f32 v89, v90, v91
	v_cvt_pk_bf16_f32 v90, v92, v93
	v_cvt_pk_bf16_f32 v91, v94, v95
	s_nop 1
	s_waitcnt lgkmcnt(6)
	v_mfma_f32_32x32x16_bf16 v[0:15], v[88:91], v[180:183], v[0:15]
	s_waitcnt lgkmcnt(4)
	v_mfma_f32_32x32x16_bf16 v[16:31], v[88:91], v[184:187], v[16:31]
	s_waitcnt lgkmcnt(2)
	v_mfma_f32_32x32x16_bf16 v[32:47], v[88:91], v[188:191], v[32:47]
	s_waitcnt lgkmcnt(0)
	v_mfma_f32_32x32x16_bf16 v[48:63], v[88:91], v[192:195], v[48:63]
